# tile placement W: the 256 out-proj weight conversion tiles moved from the P2 tail (WGs>=64) to the P7 retention WGs (needed only at P9)
# speedup vs baseline: 1.0026x; 1.0026x over previous
; __device__ __forceinline__ void tconv_list(const float* wg, const float* wu, const float* wd, const float* win, const float* wout, unsigned char* ws, const int ntiles, LAS float* t, const int wv) {
;     ...
;     for (; i < ntiles; i += G) {
;         const TDesc d = tconv_desc(wg, wu, wd, win, wout, ws, i);
;         { const TDesc dn = tconv_desc(wg, wu, wd, win, wout, ws, i + G < ntiles ? i + G : i);
; #pragma unroll
;             for (int e = 0; e < 8; ++e) { const int idx = e * 512 + tid, r = idx >> 6, c = idx & 63; nxt[e] = __builtin_nontemporal_load(dn.W + (size_t)(dn.k0 + r) * dn.N + dn.n0 + c); } }
.Ltc3_loop:
	s_add_u32 s4, s4, 192
	s_cmp_lt_u32 s4, 960
	s_cselect_b32 s31, 1, 0
	s_cbranch_scc0 .Ltc3_nonexta
	v_writelane_b32 v40, s8, 32
	v_writelane_b32 v40, s9, 33
	s_cmp_lt_u32 s4, 960
	s_cbranch_scc0 .Ltc3_seg1_1
	s_mov_b32 s7, s4
	s_and_b32 s8, s7, 15
	s_lshr_b32 s9, s7, 4
	s_mul_i32 s7, s8, 983040
	s_lshl_b32 s29, s9, 8
	s_add_u32 s7, s7, s29
	s_mul_i32 s29, s28, 15360
	s_add_u32 s7, s7, s29
	s_add_u32 s10, s18, s7
	s_addc_u32 s11, s19, 0
	s_lshl_b32 s7, s9, 6
	s_mul_i32 s7, s7, 2048
	s_lshl_b32 s29, s8, 7
	s_add_u32 s7, s7, s29
	s_mul_i32 s29, s28, 4096
	s_add_u32 s7, s7, s29
	s_add_u32 s12, s24, 0x3c4800
	s_addc_u32 s13, s25, 0
	s_add_u32 s12, s12, s7
	s_addc_u32 s13, s13, 0
	s_mov_b32 s14, 122880
	s_mov_b32 s15, 32768
	s_movk_i32 s16, 2048
	s_branch .Ltc3_segend_1

; __device__ __forceinline__ unsigned cvt_pk_bf16(float lo, float hi) { const f32x2_t v = {lo, hi}; const bf16x2_t b = __builtin_convertvector(v, bf16x2_t); return __builtin_bit_cast(unsigned, b); }
; __device__ __forceinline__ void tconv_list(const float* wg, const float* wu, const float* wd, const float* win, const float* wout, unsigned char* ws, const int ntiles, LAS float* t, const int wv) {
;     ...
; #pragma unroll
;         for (int e = 0; e < 8; ++e) { const int idx = e * 512 + tid, r = idx >> 6, c = idx & 63; t[r * 65 + c] = cur[e]; }
;         __syncthreads();
; #pragma unroll
;         for (int e = 0; e < 4; ++e) { const int idx = e * 512 + tid, n = idx >> 5, kp = idx & 31;
;             const unsigned w = pg8::cvt_pk_bf16(t[(2 * kp) * 65 + n], t[(2 * kp + 1) * 65 + n]);
;             *(unsigned*)(d.Bt + (size_t)(d.brow0 + n) * d.K + d.k0 + 2 * kp) = w; }
;         __syncthreads();
; #pragma unroll
;         for (int e = 0; e < 8; ++e) cur[e] = nxt[e];
.Ltc3_havea:
	ds_write_b32 v5, v8 offset:0
	ds_write_b32 v5, v9 offset:2080
	ds_write_b32 v5, v10 offset:4160
	ds_write_b32 v5, v11 offset:6240
	ds_write_b32 v5, v12 offset:8320
	ds_write_b32 v5, v13 offset:10400
	ds_write_b32 v5, v14 offset:12480
	ds_write_b32 v5, v15 offset:14560
	v_mad_u32_u24 v4, v2, s30, v3
	s_waitcnt lgkmcnt(0)
	s_barrier
	ds_read2_b32 v[24:25], v6 offset0:0 offset1:65
	ds_read2_b32 v[26:27], v6 offset0:16 offset1:81
	ds_read2_b32 v[28:29], v6 offset0:32 offset1:97
	ds_read2_b32 v[30:31], v6 offset0:48 offset1:113
	s_waitcnt lgkmcnt(3)
	v_cvt_pk_bf16_f32 v32, v24, v25
	s_waitcnt lgkmcnt(2)
	v_cvt_pk_bf16_f32 v33, v26, v27
	s_waitcnt lgkmcnt(1)
	v_cvt_pk_bf16_f32 v34, v28, v29
	s_waitcnt lgkmcnt(0)
	v_cvt_pk_bf16_f32 v35, v30, v31
	global_store_dword v4, v32, s[8:9]
	s_add_u32 s8, s8, s17
	s_addc_u32 s9, s9, 0
	global_store_dword v4, v33, s[8:9]
	s_add_u32 s8, s8, s17
	s_addc_u32 s9, s9, 0
	global_store_dword v4, v34, s[8:9]
	s_add_u32 s8, s8, s17
	s_addc_u32 s9, s9, 0
	global_store_dword v4, v35, s[8:9]
	s_barrier
	s_cmp_eq_u32 s31, 0
	s_cbranch_scc1 .Ltc3_done
	s_mov_b32 s17, s15
	s_mov_b32 s30, s16
	s_mov_b64 s[8:9], s[12:13]
	s_add_u32 s4, s4, 192
	s_cmp_lt_u32 s4, 960
	s_cselect_b32 s31, 1, 0
	s_cbranch_scc0 .Ltc3_nonextb
	v_writelane_b32 v40, s8, 32
	v_writelane_b32 v40, s9, 33
	s_cmp_lt_u32 s4, 960
	s_cbranch_scc0 .Ltc3_seg1_2
	s_mov_b32 s7, s4
	s_and_b32 s8, s7, 15
	s_lshr_b32 s9, s7, 4
	s_mul_i32 s7, s8, 983040
	s_lshl_b32 s29, s9, 8
	s_add_u32 s7, s7, s29
	s_mul_i32 s29, s28, 15360
	s_add_u32 s7, s7, s29
	s_add_u32 s10, s18, s7
	s_addc_u32 s11, s19, 0
	s_lshl_b32 s7, s9, 6
	s_mul_i32 s7, s7, 2048
	s_lshl_b32 s29, s8, 7
	s_add_u32 s7, s7, s29
	s_mul_i32 s29, s28, 4096
	s_add_u32 s7, s7, s29
	s_add_u32 s12, s24, 0x3c4800
	s_addc_u32 s13, s25, 0
	s_add_u32 s12, s12, s7
	s_addc_u32 s13, s13, 0
	s_mov_b32 s14, 122880
	s_mov_b32 s15, 32768
	s_movk_i32 s16, 2048
	s_branch .Ltc3_segend_2

; __device__ __forceinline__ int fresh_tid(int wv) { int l; asm volatile("v_mbcnt_lo_u32_b32 %0, -1, 0\n\tv_mbcnt_hi_u32_b32 %0, -1, %0" : "=v"(l)); return wv * 64 + l; }
; #define LAS __attribute__((address_space(3)))
; __device__ __forceinline__ void tconv_list(const float* wg, const float* wu, const float* wd, const float* win, const float* wout, unsigned char* ws, const int ntiles, LAS float* t, const int wv) {
;     const int tid = fresh_tid(wv); const int G = gridDim.x;
;     float cur[8], nxt[8];
;     int i = blockIdx.x;
;     if (i < ntiles) { const TDesc d = tconv_desc(wg, wu, wd, win, wout, ws, i);
; #pragma unroll
;         for (int e = 0; e < 8; ++e) { const int idx = e * 512 + tid, r = idx >> 6, c = idx & 63; cur[e] = __builtin_nontemporal_load(d.W + (size_t)(d.k0 + r) * d.N + d.n0 + c); } }
; __global__ void __launch_bounds__(512, 2) hymba_mega(Params P_unused) {
;     ...
;         for (int u = ob; u < 2560; u += 128) { if (u < 2048) rwkv_unit<true>(P, ldsf, u >> 4, (u >> 1) & 7, u & 1, wv); else ret_sample_unit(P, ldsf, (u - 2048) >> 2, (u - 2048) & 3, wv); }
.Ltc2_skip:
	s_cmp_lt_u32 s2, 128
	s_cbranch_scc1 .Ltc9_skip
	v_writelane_b32 v40, s4, 4
	v_writelane_b32 v40, s5, 5
	v_writelane_b32 v40, s6, 6
	v_writelane_b32 v40, s7, 7
	v_writelane_b32 v40, s8, 8
	v_writelane_b32 v40, s9, 9
	v_writelane_b32 v40, s10, 10
	v_writelane_b32 v40, s11, 11
	v_writelane_b32 v40, s12, 12
	v_writelane_b32 v40, s13, 13
	v_writelane_b32 v40, s14, 14
	v_writelane_b32 v40, s15, 15
	v_writelane_b32 v40, s16, 16
	v_writelane_b32 v40, s17, 17
	v_writelane_b32 v40, s18, 18
	v_writelane_b32 v40, s19, 19
	v_writelane_b32 v40, s20, 20
	v_writelane_b32 v40, s21, 21
	v_writelane_b32 v40, s22, 22
	v_writelane_b32 v40, s23, 23
	v_writelane_b32 v40, s24, 24
	v_writelane_b32 v40, s25, 25
	v_writelane_b32 v40, s26, 26
	v_writelane_b32 v40, s27, 27
	v_writelane_b32 v40, s28, 28
	v_writelane_b32 v40, s29, 29
	v_writelane_b32 v40, s30, 30
	v_writelane_b32 v40, s31, 31
	s_load_dwordx2 s[24:25], s[38:39], 0xd8
	s_load_dwordx2 s[26:27], s[38:39], 0xd0
	s_load_dwordx2 s[18:19], s[38:39], 0x48
	s_load_dwordx2 s[20:21], s[38:39], 0xb0
	v_mbcnt_lo_u32_b32 v0, -1, 0
	v_mbcnt_hi_u32_b32 v0, -1, v0
	s_lshr_b32 s28, s33, 6
	v_lshlrev_b32_e32 v1, 2, v0
	v_lshrrev_b32_e32 v2, 5, v0
	v_and_b32_e32 v3, 31, v0
	s_mul_i32 s7, s28, 260
	v_add_u32_e32 v5, s7, v1
	v_mul_u32_u24_e32 v6, 0x208, v3
	s_lshl_b32 s7, s28, 3
	v_lshl_add_u32 v6, v2, 2, v6
	v_add_u32_e32 v6, s7, v6
	v_lshlrev_b32_e32 v3, 2, v3
	s_sub_u32 s4, s2, 128
	s_add_u32 s4, s4, 960
	s_waitcnt lgkmcnt(0)
	s_cmp_lt_u32 s4, 960
	s_cbranch_scc0 .Ltc9_seg1_0
	s_mov_b32 s7, s4
	s_and_b32 s8, s7, 15
	s_lshr_b32 s9, s7, 4
	s_mul_i32 s7, s8, 983040
	s_lshl_b32 s29, s9, 8
	s_add_u32 s7, s7, s29
	s_mul_i32 s29, s28, 15360
	s_add_u32 s7, s7, s29
	s_add_u32 s10, s18, s7
	s_addc_u32 s11, s19, 0
	s_lshl_b32 s7, s9, 6
	s_mul_i32 s7, s7, 2048
	s_lshl_b32 s29, s8, 7
	s_add_u32 s7, s7, s29
	s_mul_i32 s29, s28, 4096
	s_add_u32 s7, s7, s29
	s_add_u32 s12, s24, 0x3c4800
	s_addc_u32 s13, s25, 0
	s_add_u32 s12, s12, s7
	s_addc_u32 s13, s13, 0
	s_mov_b32 s14, 122880
	s_mov_b32 s15, 32768
	s_movk_i32 s16, 2048
	s_branch .Ltc9_segend_0

; __device__ __forceinline__ void tconv_list(const float* wg, const float* wu, const float* wd, const float* win, const float* wout, unsigned char* ws, const int ntiles, LAS float* t, const int wv) {
;     ...
;     for (; i < ntiles; i += G) {
;         const TDesc d = tconv_desc(wg, wu, wd, win, wout, ws, i);
;         { const TDesc dn = tconv_desc(wg, wu, wd, win, wout, ws, i + G < ntiles ? i + G : i);
; #pragma unroll
;             for (int e = 0; e < 8; ++e) { const int idx = e * 512 + tid, r = idx >> 6, c = idx & 63; nxt[e] = __builtin_nontemporal_load(dn.W + (size_t)(dn.k0 + r) * dn.N + dn.n0 + c); } }
.Ltc9_loop:
	s_add_u32 s4, s4, 128
	s_cmp_lt_u32 s4, 1216
	s_cselect_b32 s31, 1, 0
	s_cbranch_scc0 .Ltc9_nonexta
	v_writelane_b32 v40, s8, 32
	v_writelane_b32 v40, s9, 33
	s_cmp_lt_u32 s4, 960
	s_cbranch_scc0 .Ltc9_seg1_1
	s_mov_b32 s7, s4
	s_and_b32 s8, s7, 15
	s_lshr_b32 s9, s7, 4
	s_mul_i32 s7, s8, 983040
	s_lshl_b32 s29, s9, 8
	s_add_u32 s7, s7, s29
	s_mul_i32 s29, s28, 15360
	s_add_u32 s7, s7, s29
	s_add_u32 s10, s18, s7
	s_addc_u32 s11, s19, 0
	s_lshl_b32 s7, s9, 6
	s_mul_i32 s7, s7, 2048
	s_lshl_b32 s29, s8, 7
	s_add_u32 s7, s7, s29
	s_mul_i32 s29, s28, 4096
	s_add_u32 s7, s7, s29
	s_add_u32 s12, s24, 0x3c4800
	s_addc_u32 s13, s25, 0
	s_add_u32 s12, s12, s7
	s_addc_u32 s13, s13, 0
	s_mov_b32 s14, 122880
	s_mov_b32 s15, 32768
	s_movk_i32 s16, 2048
	s_branch .Ltc9_segend_1

; __device__ __forceinline__ unsigned cvt_pk_bf16(float lo, float hi) { const f32x2_t v = {lo, hi}; const bf16x2_t b = __builtin_convertvector(v, bf16x2_t); return __builtin_bit_cast(unsigned, b); }
; __device__ __forceinline__ void tconv_list(const float* wg, const float* wu, const float* wd, const float* win, const float* wout, unsigned char* ws, const int ntiles, LAS float* t, const int wv) {
;     ...
; #pragma unroll
;         for (int e = 0; e < 8; ++e) { const int idx = e * 512 + tid, r = idx >> 6, c = idx & 63; t[r * 65 + c] = cur[e]; }
;         __syncthreads();
; #pragma unroll
;         for (int e = 0; e < 4; ++e) { const int idx = e * 512 + tid, n = idx >> 5, kp = idx & 31;
;             const unsigned w = pg8::cvt_pk_bf16(t[(2 * kp) * 65 + n], t[(2 * kp + 1) * 65 + n]);
;             *(unsigned*)(d.Bt + (size_t)(d.brow0 + n) * d.K + d.k0 + 2 * kp) = w; }
;         __syncthreads();
; #pragma unroll
;         for (int e = 0; e < 8; ++e) cur[e] = nxt[e];
.Ltc9_havea:
	ds_write_b32 v5, v8 offset:0
	ds_write_b32 v5, v9 offset:2080
	ds_write_b32 v5, v10 offset:4160
	ds_write_b32 v5, v11 offset:6240
	ds_write_b32 v5, v12 offset:8320
	ds_write_b32 v5, v13 offset:10400
	ds_write_b32 v5, v14 offset:12480
	ds_write_b32 v5, v15 offset:14560
	v_mad_u32_u24 v4, v2, s30, v3
	s_waitcnt lgkmcnt(0)
	s_barrier
	ds_read2_b32 v[24:25], v6 offset0:0 offset1:65
	ds_read2_b32 v[26:27], v6 offset0:16 offset1:81
	ds_read2_b32 v[28:29], v6 offset0:32 offset1:97
	ds_read2_b32 v[30:31], v6 offset0:48 offset1:113
	s_waitcnt lgkmcnt(3)
	v_cvt_pk_bf16_f32 v32, v24, v25
	s_waitcnt lgkmcnt(2)
	v_cvt_pk_bf16_f32 v33, v26, v27
	s_waitcnt lgkmcnt(1)
	v_cvt_pk_bf16_f32 v34, v28, v29
	s_waitcnt lgkmcnt(0)
	v_cvt_pk_bf16_f32 v35, v30, v31
	global_store_dword v4, v32, s[8:9]
	s_add_u32 s8, s8, s17
	s_addc_u32 s9, s9, 0
	global_store_dword v4, v33, s[8:9]
	s_add_u32 s8, s8, s17
	s_addc_u32 s9, s9, 0
	global_store_dword v4, v34, s[8:9]
	s_add_u32 s8, s8, s17
	s_addc_u32 s9, s9, 0
	global_store_dword v4, v35, s[8:9]
	s_barrier
	s_cmp_eq_u32 s31, 0
	s_cbranch_scc1 .Ltc9_done
	s_mov_b32 s17, s15
	s_mov_b32 s30, s16
	s_mov_b64 s[8:9], s[12:13]
	s_add_u32 s4, s4, 128
	s_cmp_lt_u32 s4, 1216
	s_cselect_b32 s31, 1, 0
	s_cbranch_scc0 .Ltc9_nonextb
	v_writelane_b32 v40, s8, 32
	v_writelane_b32 v40, s9, 33
	s_cmp_lt_u32 s4, 960
	s_cbranch_scc0 .Ltc9_seg1_2
	s_mov_b32 s7, s4
	s_and_b32 s8, s7, 15
	s_lshr_b32 s9, s7, 4
	s_mul_i32 s7, s8, 983040
	s_lshl_b32 s29, s9, 8
	s_add_u32 s7, s7, s29
	s_mul_i32 s29, s28, 15360
	s_add_u32 s7, s7, s29
	s_add_u32 s10, s18, s7
	s_addc_u32 s11, s19, 0
	s_lshl_b32 s7, s9, 6
	s_mul_i32 s7, s7, 2048
	s_lshl_b32 s29, s8, 7
	s_add_u32 s7, s7, s29
	s_mul_i32 s29, s28, 4096
	s_add_u32 s7, s7, s29
	s_add_u32 s12, s24, 0x3c4800
	s_addc_u32 s13, s25, 0
	s_add_u32 s12, s12, s7
	s_addc_u32 s13, s13, 0
	s_mov_b32 s14, 122880
	s_mov_b32 s15, 32768
	s_movk_i32 s16, 2048
	s_branch .Ltc9_segend_2
